# attention row-max butterflies via v_permlane16/32_swap instead of ds_bpermute
# speedup vs baseline: 1.0126x; 1.0008x over previous
; DEV f32x4 mfma16(bf16x8 a, bf16x8 b, f32x4 c) { return __builtin_amdgcn_mfma_f32_16x16x32_bf16(a, b, c, 0, 0, 0); }
; __device__ __forceinline__ void ph_attn(const P& p, int need_ctx, char* smem) {
;     ...
;       f32x4 s[2][4];
;       __builtin_amdgcn_s_setprio(1);
; #pragma unroll
;       for (int nt = 0; nt < 4; nt++) {
;         s[0][nt] = (f32x4){0.f, 0.f, 0.f, 0.f}; s[1][nt] = (f32x4){0.f, 0.f, 0.f, 0.f};
; #pragma unroll
;         for (int ks = 0; ks < 3; ks++) {
;           bf16x8 kf = *(const bf16x8*)(sK + (nt * 16 + lr) * 104 + ks * 32 + lq * 8);
;           s[0][nt] = mfma16(kf, qf[0][ks], s[0][nt]);
;           s[1][nt] = mfma16(kf, qf[1][ks], s[1][nt]);
;         }
;       }
;       __builtin_amdgcn_s_setprio(0);
;       bf16x8 pf[2][2];
; #pragma unroll
;       for (int qs = 0; qs < 2; qs++) {
;         float mx = s[qs][0][0];
; #pragma unroll
;         for (int nt = 0; nt < 4; nt++)
; #pragma unroll
;           for (int r = 0; r < 4; r++) mx = fmaxf(mx, s[qs][nt][r]);
;         mx = fmaxf(mx, __shfl_xor(mx, 16, 64)); mx = fmaxf(mx, __shfl_xor(mx, 32, 64));
;         float mn = fmaxf(m[qs], mx);
;         float alpha = __builtin_amdgcn_exp2f(m[qs] - mn);
;         m[qs] = mn;
;         float ps = 0.f;
; #pragma unroll
;         for (int nt = 0; nt < 4; nt++)
; #pragma unroll
;           for (int r = 0; r < 4; r++) { float e = __builtin_amdgcn_exp2f(s[qs][nt][r] - mn); s[qs][nt][r] = e; ps += e; }
;         lsum[qs] = lsum[qs] * alpha + ps;
.LBB0_1259:
	s_setprio 1
	ds_read_b128 v[142:145], v129
	ds_read_b128 v[150:153], v129 offset:64
	s_waitcnt lgkmcnt(1)
	v_mfma_f32_16x16x32_bf16 v[146:149], v[142:145], v[0:3], 0
	ds_read_b128 v[158:161], v129 offset:3392
	ds_read_b128 v[166:169], v129 offset:6720
	ds_read_b128 v[174:177], v129 offset:10048
	v_mfma_f32_16x16x32_bf16 v[142:145], v[142:145], v[12:15], 0
	s_waitcnt lgkmcnt(3)
	v_mfma_f32_16x16x32_bf16 v[146:149], v[150:153], v[4:7], v[146:149]
	v_mfma_f32_16x16x32_bf16 v[142:145], v[150:153], v[16:19], v[142:145]
	ds_read_b128 v[150:153], v129 offset:128
	s_waitcnt lgkmcnt(0)
	v_mfma_f32_16x16x32_bf16 v[146:149], v[150:153], v[8:11], v[146:149]
	v_mfma_f32_16x16x32_bf16 v[142:145], v[150:153], v[20:23], v[142:145]
	ds_read_b128 v[150:153], v129 offset:3328
	s_waitcnt lgkmcnt(0)
	v_mfma_f32_16x16x32_bf16 v[154:157], v[150:153], v[0:3], 0
	v_mfma_f32_16x16x32_bf16 v[150:153], v[150:153], v[12:15], 0
	v_mfma_f32_16x16x32_bf16 v[154:157], v[158:161], v[4:7], v[154:157]
	v_mfma_f32_16x16x32_bf16 v[150:153], v[158:161], v[16:19], v[150:153]
	ds_read_b128 v[158:161], v129 offset:3456
	s_waitcnt lgkmcnt(0)
	v_mfma_f32_16x16x32_bf16 v[154:157], v[158:161], v[8:11], v[154:157]
	v_mfma_f32_16x16x32_bf16 v[150:153], v[158:161], v[20:23], v[150:153]
	ds_read_b128 v[158:161], v129 offset:6656
	s_waitcnt lgkmcnt(0)
	v_mfma_f32_16x16x32_bf16 v[162:165], v[158:161], v[0:3], 0
	v_mfma_f32_16x16x32_bf16 v[158:161], v[158:161], v[12:15], 0
	v_mfma_f32_16x16x32_bf16 v[162:165], v[166:169], v[4:7], v[162:165]
	v_mfma_f32_16x16x32_bf16 v[158:161], v[166:169], v[16:19], v[158:161]
	ds_read_b128 v[166:169], v129 offset:6784
	s_waitcnt lgkmcnt(0)
	v_mfma_f32_16x16x32_bf16 v[162:165], v[166:169], v[8:11], v[162:165]
	v_mfma_f32_16x16x32_bf16 v[158:161], v[166:169], v[20:23], v[158:161]
	ds_read_b128 v[166:169], v129 offset:9984
	s_waitcnt lgkmcnt(0)
	v_mfma_f32_16x16x32_bf16 v[170:173], v[166:169], v[0:3], 0
	v_mfma_f32_16x16x32_bf16 v[166:169], v[166:169], v[12:15], 0
	v_mfma_f32_16x16x32_bf16 v[170:173], v[174:177], v[4:7], v[170:173]
	v_mfma_f32_16x16x32_bf16 v[166:169], v[174:177], v[16:19], v[166:169]
	ds_read_b128 v[174:177], v129 offset:10112
	s_waitcnt lgkmcnt(0)
	v_mfma_f32_16x16x32_bf16 v[170:173], v[174:177], v[8:11], v[170:173]
	v_mfma_f32_16x16x32_bf16 v[166:169], v[174:177], v[20:23], v[166:169]
	s_setprio 0
	v_max_f32_e32 v141, v147, v147
	v_max_f32_e32 v174, v146, v146
	v_max_f32_e32 v141, v174, v141
	v_max3_f32 v141, v141, v148, v149
	v_max3_f32 v141, v141, v154, v155
	v_max3_f32 v141, v141, v156, v157
	v_max3_f32 v141, v141, v162, v163
	v_max3_f32 v141, v141, v164, v165
	v_max3_f32 v141, v141, v170, v171
	v_max3_f32 v141, v141, v172, v173
	v_mov_b32_e32 v174, v141
	s_nop 1
	v_permlane16_swap_b32_e32 v141, v174
	v_max_f32_e32 v141, v141, v174
	v_mov_b32_e32 v174, v141
	s_nop 1
	v_permlane32_swap_b32_e32 v141, v174
	v_max3_f32 v194, v140, v141, v174
	v_sub_f32_e32 v140, v140, v194
	v_sub_f32_e32 v141, v146, v194
	v_sub_f32_e32 v146, v147, v194
	v_sub_f32_e32 v147, v148, v194
	v_exp_f32_e32 v148, v140
	v_sub_f32_e32 v140, v154, v194
	v_exp_f32_e32 v154, v140
	v_sub_f32_e32 v140, v155, v194
	v_exp_f32_e32 v182, v140
	v_sub_f32_e32 v140, v156, v194
	v_exp_f32_e32 v156, v140
	v_sub_f32_e32 v140, v157, v194
	v_exp_f32_e32 v184, v140
	v_sub_f32_e32 v140, v162, v194
	v_exp_f32_e32 v162, v140
	v_sub_f32_e32 v140, v163, v194
	v_exp_f32_e32 v186, v140
	v_sub_f32_e32 v140, v164, v194
	v_exp_f32_e32 v164, v140
	v_sub_f32_e32 v140, v165, v194
	v_exp_f32_e32 v174, v141
	v_exp_f32_e32 v188, v140
	v_max_f32_e32 v140, v143, v143
	v_max_f32_e32 v141, v142, v142
	v_max_f32_e32 v140, v141, v140
	v_max3_f32 v140, v140, v144, v145
	v_max3_f32 v140, v140, v150, v151
	v_max3_f32 v140, v140, v152, v153
	v_max3_f32 v140, v140, v158, v159
	v_max3_f32 v140, v140, v160, v161
	v_max3_f32 v140, v140, v166, v167
	v_max3_f32 v140, v140, v168, v169
	v_mov_b32_e32 v141, v140
	v_sub_f32_e32 v149, v149, v194
	v_exp_f32_e32 v180, v149
	v_permlane16_swap_b32_e32 v140, v141
	v_exp_f32_e32 v176, v146
	v_exp_f32_e32 v178, v147
	v_max_f32_e32 v140, v140, v141
	v_mov_b32_e32 v141, v140
	v_sub_f32_e32 v146, v170, v194
	v_exp_f32_e32 v170, v146
	v_permlane32_swap_b32_e32 v140, v141
	v_sub_f32_e32 v146, v171, v194
	v_exp_f32_e32 v190, v146
	v_max3_f32 v195, v135, v140, v141
	v_sub_f32_e32 v135, v135, v195
	v_exp_f32_e32 v149, v135
	v_sub_f32_e32 v135, v142, v195
	v_exp_f32_e32 v175, v135
	v_sub_f32_e32 v135, v143, v195
	v_exp_f32_e32 v177, v135
	v_sub_f32_e32 v135, v144, v195
	v_exp_f32_e32 v179, v135
	v_sub_f32_e32 v135, v145, v195
	v_exp_f32_e32 v181, v135
	v_sub_f32_e32 v135, v150, v195
	v_exp_f32_e32 v155, v135
	v_sub_f32_e32 v135, v151, v195
	v_pk_add_f32 v[144:145], v[174:175], 0 op_sel_hi:[1,0]
	v_exp_f32_e32 v183, v135
	v_pk_add_f32 v[144:145], v[176:177], v[144:145]
	v_sub_f32_e32 v135, v152, v195
	v_pk_add_f32 v[144:145], v[178:179], v[144:145]
	v_exp_f32_e32 v157, v135
	v_sub_f32_e32 v135, v153, v195
	v_pk_add_f32 v[144:145], v[180:181], v[144:145]
; DEV f32x4 mfma16(bf16x8 a, bf16x8 b, f32x4 c) { return __builtin_amdgcn_mfma_f32_16x16x32_bf16(a, b, c, 0, 0, 0); }
; __device__ __forceinline__ void ph_attn(const P& p, int need_ctx, char* smem) {
;     ...
;         mx = fmaxf(mx, __shfl_xor(mx, 16, 64)); mx = fmaxf(mx, __shfl_xor(mx, 32, 64));
;         float mn = fmaxf(m[qs], mx);
;         float alpha = __builtin_amdgcn_exp2f(m[qs] - mn);
;         m[qs] = mn;
;         float ps = 0.f;
; #pragma unroll
;         for (int nt = 0; nt < 4; nt++)
; #pragma unroll
;           for (int r = 0; r < 4; r++) { float e = __builtin_amdgcn_exp2f(s[qs][nt][r] - mn); s[qs][nt][r] = e; ps += e; }
;         lsum[qs] = lsum[qs] * alpha + ps;
; #pragma unroll
;         for (int nt = 0; nt < 4; nt++)
; #pragma unroll
;           for (int r = 0; r < 4; r++) o[qs][nt][r] *= alpha;
; #pragma unroll
;         for (int m2 = 0; m2 < 2; m2++) {
;           u32x4 w;
;           w[0] = pack2(s[qs][2 * m2][0], s[qs][2 * m2][1]); w[1] = pack2(s[qs][2 * m2][2], s[qs][2 * m2][3]);
;           w[2] = pack2(s[qs][2 * m2 + 1][0], s[qs][2 * m2 + 1][1]); w[3] = pack2(s[qs][2 * m2 + 1][2], s[qs][2 * m2 + 1][3]);
;           pf[qs][m2] = __builtin_bit_cast(bf16x8, w);
;         }
;       }
;       __builtin_amdgcn_s_setprio(1);
; #pragma unroll
;       for (int m2 = 0; m2 < 2; m2++) {
; #pragma unroll
;         for (int nt = 0; nt < 4; nt++) {
;           const u16* vp = sV + (nt * 16 + lr) * 72 + 32 * m2 + 4 * lq;
;           uint2 lo = *(const uint2*)vp, hi = *(const uint2*)(vp + 16);
;           u32x4 w; w[0] = lo.x; w[1] = lo.y; w[2] = hi.x; w[3] = hi.y;
;           bf16x8 vf = __builtin_bit_cast(bf16x8, w);
;           o[0][nt] = mfma16(vf, pf[0][m2], o[0][nt]);
;           o[1][nt] = mfma16(vf, pf[1][m2], o[1][nt]);
;         }
;       }
;       __builtin_amdgcn_s_setprio(0);
	v_exp_f32_e32 v185, v135
	v_sub_f32_e32 v135, v158, v195
	v_pk_add_f32 v[144:145], v[154:155], v[144:145]
	v_exp_f32_e32 v163, v135
	v_sub_f32_e32 v135, v159, v195
	v_pk_add_f32 v[150:151], v[182:183], v[144:145]
	v_exp_f32_e32 v187, v135
	v_sub_f32_e32 v135, v160, v195
	v_exp_f32_e32 v165, v135
	v_sub_f32_e32 v135, v161, v195
	v_pk_add_f32 v[150:151], v[156:157], v[150:151]
	v_exp_f32_e32 v189, v135
	v_sub_f32_e32 v135, v166, v195
	v_pk_add_f32 v[150:151], v[184:185], v[150:151]
	v_exp_f32_e32 v171, v135
	v_sub_f32_e32 v135, v167, v195
	v_pk_add_f32 v[150:151], v[162:163], v[150:151]
	v_sub_f32_e32 v146, v172, v194
	v_exp_f32_e32 v191, v135
	v_sub_f32_e32 v135, v168, v195
	v_pk_add_f32 v[150:151], v[186:187], v[150:151]
	v_exp_f32_e32 v172, v146
	v_sub_f32_e32 v146, v173, v194
	v_exp_f32_e32 v173, v135
	v_sub_f32_e32 v135, v169, v195
	v_pk_add_f32 v[150:151], v[164:165], v[150:151]
	v_exp_f32_e32 v192, v146
	v_exp_f32_e32 v193, v135
	v_pk_add_f32 v[150:151], v[188:189], v[150:151]
	v_pk_mul_f32 v[74:75], v[74:75], v[148:149] op_sel_hi:[1,0]
	v_pk_add_f32 v[150:151], v[170:171], v[150:151]
	v_pk_mul_f32 v[72:73], v[72:73], v[148:149] op_sel_hi:[1,0]
	v_pk_add_f32 v[150:151], v[190:191], v[150:151]
	v_pk_mul_f32 v[70:71], v[70:71], v[148:149] op_sel_hi:[1,0]
	v_pk_add_f32 v[150:151], v[172:173], v[150:151]
	v_pk_mul_f32 v[68:69], v[68:69], v[148:149] op_sel_hi:[1,0]
	v_pk_add_f32 v[150:151], v[192:193], v[150:151]
	v_pk_mul_f32 v[66:67], v[66:67], v[148:149] op_sel_hi:[1,0]
	v_pk_mul_f32 v[64:65], v[64:65], v[148:149] op_sel_hi:[1,0]
	v_pk_mul_f32 v[62:63], v[62:63], v[148:149] op_sel_hi:[1,0]
	v_pk_mul_f32 v[60:61], v[60:61], v[148:149] op_sel_hi:[1,0]
	v_pk_fma_f32 v[106:107], v[106:107], v[148:149], v[150:151]
	v_mov_b32_e32 v148, v149
	v_cvt_pk_bf16_f32 v140, v174, v176
	v_pk_mul_f32 v[58:59], v[58:59], v[148:149] op_sel_hi:[1,0]
	v_pk_mul_f32 v[56:57], v[56:57], v[148:149] op_sel_hi:[1,0]
	v_pk_mul_f32 v[54:55], v[54:55], v[148:149] op_sel_hi:[1,0]
	v_pk_mul_f32 v[52:53], v[52:53], v[148:149] op_sel_hi:[1,0]
	v_pk_mul_f32 v[50:51], v[50:51], v[148:149] op_sel_hi:[1,0]
	v_pk_mul_f32 v[48:49], v[48:49], v[148:149] op_sel_hi:[1,0]
	v_pk_mul_f32 v[46:47], v[46:47], v[148:149] op_sel_hi:[1,0]
	v_pk_mul_f32 v[44:45], v[44:45], v[148:149] op_sel_hi:[1,0]
	v_cvt_pk_bf16_f32 v141, v178, v180
	v_cvt_pk_bf16_f32 v142, v154, v182
	v_cvt_pk_bf16_f32 v143, v156, v184
	v_cvt_pk_bf16_f32 v144, v162, v186
	v_cvt_pk_bf16_f32 v145, v164, v188
	v_cvt_pk_bf16_f32 v146, v170, v190
	v_cvt_pk_bf16_f32 v147, v172, v192
	v_cvt_pk_bf16_f32 v148, v175, v177
	v_cvt_pk_bf16_f32 v149, v179, v181
	v_cvt_pk_bf16_f32 v150, v155, v183
	v_cvt_pk_bf16_f32 v151, v157, v185
	v_cvt_pk_bf16_f32 v152, v163, v187
	v_cvt_pk_bf16_f32 v153, v165, v189
	v_cvt_pk_bf16_f32 v154, v171, v191
	v_cvt_pk_bf16_f32 v155, v173, v193
	s_setprio 1
	v_add_u32_e32 v135, 0x3000, v131
	ds_read2_b64 v[156:159], v135 offset0:128 offset1:132
	v_add_u32_e32 v160, 0x3000, v132
	v_add_u32_e32 v161, 0x3800, v132
	v_add_u32_e32 v162, 0x4000, v132
	s_waitcnt lgkmcnt(0)
	v_mfma_f32_16x16x32_bf16 v[72:75], v[156:159], v[140:143], v[72:75]
	v_mfma_f32_16x16x32_bf16 v[56:59], v[156:159], v[148:151], v[56:59]
	ds_read2_b64 v[156:159], v160 offset0:128 offset1:132
	s_waitcnt lgkmcnt(0)
	v_mfma_f32_16x16x32_bf16 v[68:71], v[156:159], v[140:143], v[68:71]
	v_mfma_f32_16x16x32_bf16 v[52:55], v[156:159], v[148:151], v[52:55]
	ds_read2_b64 v[156:159], v161 offset0:160 offset1:164
	s_waitcnt lgkmcnt(0)
	v_mfma_f32_16x16x32_bf16 v[64:67], v[156:159], v[140:143], v[64:67]
	v_mfma_f32_16x16x32_bf16 v[48:51], v[156:159], v[148:151], v[48:51]
	ds_read2_b64 v[156:159], v162 offset0:192 offset1:196
	s_waitcnt lgkmcnt(0)
	v_mfma_f32_16x16x32_bf16 v[60:63], v[156:159], v[140:143], v[60:63]
	ds_read2_b64 v[140:143], v135 offset0:136 offset1:140
	s_waitcnt lgkmcnt(0)
	v_mfma_f32_16x16x32_bf16 v[72:75], v[140:143], v[144:147], v[72:75]
	v_mfma_f32_16x16x32_bf16 v[56:59], v[140:143], v[152:155], v[56:59]
	ds_read2_b64 v[140:143], v160 offset0:136 offset1:140
	s_waitcnt lgkmcnt(0)
	v_mfma_f32_16x16x32_bf16 v[68:71], v[140:143], v[144:147], v[68:71]
	v_mfma_f32_16x16x32_bf16 v[52:55], v[140:143], v[152:155], v[52:55]
	ds_read2_b64 v[140:143], v161 offset0:168 offset1:172
	s_waitcnt lgkmcnt(0)
	v_mfma_f32_16x16x32_bf16 v[64:67], v[140:143], v[144:147], v[64:67]
	v_mfma_f32_16x16x32_bf16 v[48:51], v[140:143], v[152:155], v[48:51]
	ds_read2_b64 v[140:143], v162 offset0:200 offset1:204
	v_mfma_f32_16x16x32_bf16 v[44:47], v[156:159], v[148:151], v[44:47]
	s_waitcnt lgkmcnt(0)
	v_mfma_f32_16x16x32_bf16 v[60:63], v[140:143], v[144:147], v[60:63]
	v_mfma_f32_16x16x32_bf16 v[44:47], v[140:143], v[152:155], v[44:47]
	s_setprio 0
	s_add_i32 s0, s0, 64
	s_add_i32 s1, s1, 64
	v_lshl_add_u64 v[114:115], v[114:115], 0, s[30:31]
	v_lshl_add_u64 v[116:117], v[116:117], 0, s[30:31]
	s_cmp_eq_u32 s21, s3
	s_mov_b32 s22, s3
	v_mov_b32_e32 v140, v194
	v_mov_b32_e32 v135, v195
	s_cbranch_scc1 .LBB0_1241
